# attention fast path loop edge: when the next key tile is a regular tile the tile barrier and loop bookkeeping run inline and control goes straight to the deferred entry (4 fewer taken branches per til
# speedup vs baseline: 1.0053x; 1.0053x over previous
.Latt_a_main:
	s_waitcnt lgkmcnt(6)
	v_mfma_f32_32x32x16_bf16 v[132:147], v[180:183], v[184:187], v[148:163]
	ds_read_b128 v[180:183], v249
	ds_read_b128 v[184:187], v219 offset:3072
	s_waitcnt lgkmcnt(6)
	v_mfma_f32_32x32x16_bf16 v[148:163], v[188:191], v[192:195], v[148:163]
	ds_read_b128 v[188:191], v251
	ds_read_b128 v[192:195], v219 offset:5120
	s_waitcnt lgkmcnt(6)
	v_mfma_f32_32x32x16_bf16 v[148:163], v[200:203], v[204:207], v[148:163]
	ds_read_b128 v[200:203], v252
	ds_read_b128 v[204:207], v219 offset:6144
	s_waitcnt lgkmcnt(6)
	v_mfma_f32_32x32x16_bf16 v[148:163], v[208:211], v[212:215], v[148:163]
	ds_read_b128 v[208:211], v253
	ds_read_b128 v[212:215], v219 offset:7168
	s_waitcnt lgkmcnt(6)
	v_mfma_f32_32x32x16_bf16 v[148:163], v[180:183], v[184:187], v[148:163]
	ds_read_b64_tr_b16 v[180:181], v228 offset:32768
	ds_read_b64_tr_b16 v[182:183], v228 offset:33280
	ds_read_b64_tr_b16 v[184:185], v228 offset:33792
	ds_read_b64_tr_b16 v[186:187], v228 offset:34304
	s_waitcnt lgkmcnt(8)
	v_mfma_f32_32x32x16_bf16 v[132:147], v[188:191], v[192:195], v[132:147]
	ds_read_b64_tr_b16 v[188:189], v228 offset:36864
	ds_read_b64_tr_b16 v[190:191], v228 offset:37376
	ds_read_b64_tr_b16 v[192:193], v228 offset:37888
	ds_read_b64_tr_b16 v[194:195], v228 offset:38400
	s_waitcnt lgkmcnt(10)
	v_mfma_f32_32x32x16_bf16 v[132:147], v[200:203], v[204:207], v[132:147]
	ds_read_b64_tr_b16 v[200:201], v228 offset:40960
	ds_read_b64_tr_b16 v[202:203], v228 offset:41472
	ds_read_b64_tr_b16 v[204:205], v228 offset:41984
	ds_read_b64_tr_b16 v[206:207], v228 offset:42496
	s_waitcnt lgkmcnt(12)
	v_mfma_f32_32x32x16_bf16 v[132:147], v[208:211], v[212:215], v[132:147]
	ds_read_b64_tr_b16 v[208:209], v228 offset:45056
	ds_read_b64_tr_b16 v[210:211], v228 offset:45568
	v_exp_f32_e32 v148, v148
	v_exp_f32_e32 v149, v149
	v_exp_f32_e32 v150, v150
	v_exp_f32_e32 v151, v151
	v_exp_f32_e32 v152, v152
	v_exp_f32_e32 v153, v153
	v_exp_f32_e32 v154, v154
	v_exp_f32_e32 v155, v155
	v_exp_f32_e32 v156, v156
	v_exp_f32_e32 v157, v157
	v_exp_f32_e32 v158, v158
	v_exp_f32_e32 v159, v159
	v_exp_f32_e32 v160, v160
	v_exp_f32_e32 v161, v161
	v_exp_f32_e32 v162, v162
	v_exp_f32_e32 v163, v163
	v_add_f32_e32 v170, v170, v148
	v_add_f32_e32 v171, v171, v149
	v_cvt_pk_bf16_f32 v230, v148, v149
	v_add_f32_e32 v170, v170, v150
	v_add_f32_e32 v171, v171, v151
	v_cvt_pk_bf16_f32 v231, v150, v151
	v_add_f32_e32 v170, v170, v152
	v_add_f32_e32 v171, v171, v153
	v_cvt_pk_bf16_f32 v232, v152, v153
	v_add_f32_e32 v170, v170, v154
	v_add_f32_e32 v171, v171, v155
	v_cvt_pk_bf16_f32 v233, v154, v155
	v_add_f32_e32 v170, v170, v156
	v_add_f32_e32 v171, v171, v157
	v_cvt_pk_bf16_f32 v234, v156, v157
	v_add_f32_e32 v170, v170, v158
	v_add_f32_e32 v171, v171, v159
	v_cvt_pk_bf16_f32 v235, v158, v159
	v_add_f32_e32 v170, v170, v160
	v_add_f32_e32 v171, v171, v161
	v_cvt_pk_bf16_f32 v236, v160, v161
	v_add_f32_e32 v170, v170, v162
	v_add_f32_e32 v171, v171, v163
	v_cvt_pk_bf16_f32 v237, v162, v163
	s_waitcnt lgkmcnt(12)
	ds_read_b64_tr_b16 v[212:213], v228 offset:46080
	ds_read_b64_tr_b16 v[214:215], v228 offset:46592
	s_setprio 2
	v_mfma_f32_32x32x16_bf16 v[100:115], v[180:183], v[230:233], v[100:115]
	v_exp_f32_e32 v132, v132
	v_exp_f32_e32 v133, v133
	s_waitcnt lgkmcnt(12)
	v_mfma_f32_32x32x16_bf16 v[100:115], v[184:187], v[234:237], v[100:115]
	v_exp_f32_e32 v134, v134
	v_exp_f32_e32 v135, v135
	v_add_f32_e32 v178, v178, v132
	v_add_f32_e32 v179, v179, v133
	v_cvt_pk_bf16_f32 v238, v132, v133
	s_waitcnt lgkmcnt(10)
	v_mfma_f32_32x32x16_bf16 v[68:83], v[188:191], v[230:233], v[68:83]
	v_exp_f32_e32 v136, v136
	v_exp_f32_e32 v137, v137
	v_add_f32_e32 v178, v178, v134
	v_add_f32_e32 v179, v179, v135
	v_cvt_pk_bf16_f32 v239, v134, v135
	s_waitcnt lgkmcnt(8)
	v_mfma_f32_32x32x16_bf16 v[68:83], v[192:195], v[234:237], v[68:83]
	v_exp_f32_e32 v138, v138
	v_exp_f32_e32 v139, v139
	v_add_f32_e32 v178, v178, v136
	v_add_f32_e32 v179, v179, v137
	v_cvt_pk_bf16_f32 v240, v136, v137
	s_waitcnt lgkmcnt(6)
	v_mfma_f32_32x32x16_bf16 v[34:49], v[200:203], v[230:233], v[34:49]
	v_exp_f32_e32 v140, v140
	v_exp_f32_e32 v141, v141
	v_add_f32_e32 v178, v178, v138
	v_add_f32_e32 v179, v179, v139
	v_cvt_pk_bf16_f32 v241, v138, v139
	s_waitcnt lgkmcnt(4)
	v_mfma_f32_32x32x16_bf16 v[34:49], v[204:207], v[234:237], v[34:49]
	v_exp_f32_e32 v142, v142
	v_exp_f32_e32 v143, v143
	v_add_f32_e32 v178, v178, v140
	v_add_f32_e32 v179, v179, v141
	v_cvt_pk_bf16_f32 v242, v140, v141
	s_waitcnt lgkmcnt(2)
	v_mfma_f32_32x32x16_bf16 v[18:33], v[208:211], v[230:233], v[18:33]
	v_exp_f32_e32 v144, v144
	v_exp_f32_e32 v145, v145
	v_add_f32_e32 v178, v178, v142
	v_add_f32_e32 v179, v179, v143
	v_cvt_pk_bf16_f32 v243, v142, v143
	s_waitcnt lgkmcnt(0)
	v_mfma_f32_32x32x16_bf16 v[18:33], v[212:215], v[234:237], v[18:33]
	v_exp_f32_e32 v146, v146
	v_exp_f32_e32 v147, v147
	v_add_f32_e32 v178, v178, v144
	v_add_f32_e32 v179, v179, v145
	v_cvt_pk_bf16_f32 v244, v144, v145
	s_nop 0
	v_add_f32_e32 v178, v178, v146
	v_add_f32_e32 v179, v179, v147
	v_cvt_pk_bf16_f32 v245, v146, v147
	s_nop 0
	v_mfma_f32_32x32x16_bf16 v[116:131], v[180:183], v[238:241], v[116:131]
	v_add3_u32 v148, s20, v216, 32
	v_sub_u32_e32 v148, v148, v166
	v_mfma_f32_32x32x16_bf16 v[116:131], v[184:187], v[242:245], v[116:131]
	ds_read_b128 v[180:183], v250 offset:8192
	ds_read_b128 v[184:187], v219 offset:4096
	v_cvt_f32_i32_e32 v148, v148
	v_fma_f32 v148, v164, v148, -v221
	v_mfma_f32_32x32x16_bf16 v[84:99], v[188:191], v[238:241], v[84:99]
	v_add_f32_e32 v149, v164, v148
	v_add_f32_e32 v150, v176, v148
	v_add_f32_e32 v151, v177, v149
	v_mfma_f32_32x32x16_bf16 v[84:99], v[192:195], v[242:245], v[84:99]
	ds_read_b128 v[188:191], v246 offset:8192
	ds_read_b128 v[192:195], v219
	v_add_f32_e32 v152, v174, v148
	v_add_f32_e32 v153, v175, v149
	v_add_f32_e32 v154, v174, v150
	v_add_f32_e32 v155, v175, v151
	v_mfma_f32_32x32x16_bf16 v[50:65], v[200:203], v[238:241], v[50:65]
	v_add_f32_e32 v156, v174, v152
	v_add_f32_e32 v157, v175, v153
	v_add_f32_e32 v158, v174, v154
	v_add_f32_e32 v159, v175, v155
	v_mfma_f32_32x32x16_bf16 v[50:65], v[204:207], v[242:245], v[50:65]
	ds_read_b128 v[200:203], v247 offset:8192
	ds_read_b128 v[204:207], v219 offset:1024
	v_add_f32_e32 v160, v174, v156
	v_add_f32_e32 v161, v175, v157
	v_add_f32_e32 v162, v174, v158
	v_add_f32_e32 v163, v175, v159
	v_mfma_f32_32x32x16_bf16 v[2:17], v[208:211], v[238:241], v[2:17]
	v_mfma_f32_32x32x16_bf16 v[2:17], v[212:215], v[242:245], v[2:17]
	ds_read_b128 v[208:211], v248 offset:8192
	ds_read_b128 v[212:215], v219 offset:2048
	s_setprio 0
	s_waitcnt lgkmcnt(6)
	v_mfma_f32_32x32x16_bf16 v[132:147], v[180:183], v[184:187], v[148:163]
	ds_read_b128 v[180:183], v249 offset:8192
	ds_read_b128 v[184:187], v219 offset:3072
	s_waitcnt lgkmcnt(6)
	v_mfma_f32_32x32x16_bf16 v[148:163], v[188:191], v[192:195], v[148:163]
	ds_read_b128 v[188:191], v251 offset:8192
	ds_read_b128 v[192:195], v219 offset:5120
	s_waitcnt lgkmcnt(6)
	v_mfma_f32_32x32x16_bf16 v[148:163], v[200:203], v[204:207], v[148:163]
	ds_read_b128 v[200:203], v252 offset:8192
	ds_read_b128 v[204:207], v219 offset:6144
	s_waitcnt lgkmcnt(6)
	v_mfma_f32_32x32x16_bf16 v[148:163], v[208:211], v[212:215], v[148:163]
	ds_read_b128 v[208:211], v253 offset:8192
	ds_read_b128 v[212:215], v219 offset:7168
	s_waitcnt lgkmcnt(6)
	v_mfma_f32_32x32x16_bf16 v[148:163], v[180:183], v[184:187], v[148:163]
	ds_read_b64_tr_b16 v[180:181], v228 offset:34816
	ds_read_b64_tr_b16 v[182:183], v228 offset:35328
	ds_read_b64_tr_b16 v[184:185], v228 offset:35840
	ds_read_b64_tr_b16 v[186:187], v228 offset:36352
	s_waitcnt lgkmcnt(8)
	v_mfma_f32_32x32x16_bf16 v[132:147], v[188:191], v[192:195], v[132:147]
	ds_read_b64_tr_b16 v[188:189], v228 offset:38912
	ds_read_b64_tr_b16 v[190:191], v228 offset:39424
	ds_read_b64_tr_b16 v[192:193], v228 offset:39936
	ds_read_b64_tr_b16 v[194:195], v228 offset:40448
	s_waitcnt lgkmcnt(10)
	v_mfma_f32_32x32x16_bf16 v[132:147], v[200:203], v[204:207], v[132:147]
	ds_read_b64_tr_b16 v[200:201], v228 offset:43008
	ds_read_b64_tr_b16 v[202:203], v228 offset:43520
	ds_read_b64_tr_b16 v[204:205], v228 offset:44032
	ds_read_b64_tr_b16 v[206:207], v228 offset:44544
	s_waitcnt lgkmcnt(12)
	v_mfma_f32_32x32x16_bf16 v[132:147], v[208:211], v[212:215], v[132:147]
	ds_read_b64_tr_b16 v[208:209], v228 offset:47104
	ds_read_b64_tr_b16 v[210:211], v228 offset:47616
	v_exp_f32_e32 v148, v148
	v_exp_f32_e32 v149, v149
	v_exp_f32_e32 v150, v150
	v_exp_f32_e32 v151, v151
	v_exp_f32_e32 v152, v152
	v_exp_f32_e32 v153, v153
	v_exp_f32_e32 v154, v154
	v_exp_f32_e32 v155, v155
	v_exp_f32_e32 v156, v156
	v_exp_f32_e32 v157, v157
	v_exp_f32_e32 v158, v158
	v_exp_f32_e32 v159, v159
	v_exp_f32_e32 v160, v160
	v_exp_f32_e32 v161, v161
	v_exp_f32_e32 v162, v162
	v_exp_f32_e32 v163, v163
	v_add_f32_e32 v170, v170, v148
	v_add_f32_e32 v171, v171, v149
	v_cvt_pk_bf16_f32 v230, v148, v149
	v_add_f32_e32 v170, v170, v150
	v_add_f32_e32 v171, v171, v151
	v_cvt_pk_bf16_f32 v231, v150, v151
	v_add_f32_e32 v170, v170, v152
	v_add_f32_e32 v171, v171, v153
	v_cvt_pk_bf16_f32 v232, v152, v153
	v_add_f32_e32 v170, v170, v154
	v_add_f32_e32 v171, v171, v155
	v_cvt_pk_bf16_f32 v233, v154, v155
	v_add_f32_e32 v170, v170, v156
	v_add_f32_e32 v171, v171, v157
	v_cvt_pk_bf16_f32 v234, v156, v157
	v_add_f32_e32 v170, v170, v158
	v_add_f32_e32 v171, v171, v159
	v_cvt_pk_bf16_f32 v235, v158, v159
	v_add_f32_e32 v170, v170, v160
	v_add_f32_e32 v171, v171, v161
	v_cvt_pk_bf16_f32 v236, v160, v161
	v_add_f32_e32 v170, v170, v162
	v_add_f32_e32 v171, v171, v163
	v_cvt_pk_bf16_f32 v237, v162, v163
	s_waitcnt lgkmcnt(12)
	ds_read_b64_tr_b16 v[212:213], v228 offset:48128
	ds_read_b64_tr_b16 v[214:215], v228 offset:48640
	s_setprio 2
	v_mfma_f32_32x32x16_bf16 v[100:115], v[180:183], v[230:233], v[100:115]
	v_exp_f32_e32 v132, v132
	v_exp_f32_e32 v133, v133
	s_waitcnt lgkmcnt(12)
	v_mfma_f32_32x32x16_bf16 v[100:115], v[184:187], v[234:237], v[100:115]
	v_exp_f32_e32 v134, v134
	v_exp_f32_e32 v135, v135
	v_add_f32_e32 v178, v178, v132
	v_add_f32_e32 v179, v179, v133
	v_cvt_pk_bf16_f32 v238, v132, v133
	s_waitcnt lgkmcnt(10)
	v_mfma_f32_32x32x16_bf16 v[68:83], v[188:191], v[230:233], v[68:83]
	v_exp_f32_e32 v136, v136
	v_exp_f32_e32 v137, v137
	v_add_f32_e32 v178, v178, v134
	v_add_f32_e32 v179, v179, v135
	v_cvt_pk_bf16_f32 v239, v134, v135
	s_waitcnt lgkmcnt(8)
	v_mfma_f32_32x32x16_bf16 v[68:83], v[192:195], v[234:237], v[68:83]
	v_exp_f32_e32 v138, v138
	v_exp_f32_e32 v139, v139
	v_add_f32_e32 v178, v178, v136
	v_add_f32_e32 v179, v179, v137
	v_cvt_pk_bf16_f32 v240, v136, v137
	s_waitcnt lgkmcnt(6)
	v_mfma_f32_32x32x16_bf16 v[34:49], v[200:203], v[230:233], v[34:49]
	v_exp_f32_e32 v140, v140
	v_exp_f32_e32 v141, v141
	v_add_f32_e32 v178, v178, v138
	v_add_f32_e32 v179, v179, v139
	v_cvt_pk_bf16_f32 v241, v138, v139
	s_waitcnt lgkmcnt(4)
	v_mfma_f32_32x32x16_bf16 v[34:49], v[204:207], v[234:237], v[34:49]
	v_exp_f32_e32 v142, v142
	v_exp_f32_e32 v143, v143
	v_add_f32_e32 v178, v178, v140
	v_add_f32_e32 v179, v179, v141
	v_cvt_pk_bf16_f32 v242, v140, v141
	s_waitcnt lgkmcnt(2)
	v_mfma_f32_32x32x16_bf16 v[18:33], v[208:211], v[230:233], v[18:33]
	v_exp_f32_e32 v144, v144
	v_exp_f32_e32 v145, v145
	v_add_f32_e32 v178, v178, v142
	v_add_f32_e32 v179, v179, v143
	v_cvt_pk_bf16_f32 v243, v142, v143
	s_waitcnt lgkmcnt(0)
	v_mfma_f32_32x32x16_bf16 v[18:33], v[212:215], v[234:237], v[18:33]
	v_exp_f32_e32 v146, v146
	v_exp_f32_e32 v147, v147
	v_add_f32_e32 v178, v178, v144
	v_add_f32_e32 v179, v179, v145
	v_cvt_pk_bf16_f32 v244, v144, v145
	s_nop 0
	v_add_f32_e32 v178, v178, v146
	v_add_f32_e32 v179, v179, v147
	v_cvt_pk_bf16_f32 v245, v146, v147
	s_nop 0
	s_cmp_ge_i32 s13, s77
	s_cbranch_scc1 .Latt_a_flush
	s_cmp_eq_u32 s13, s78
	s_cbranch_scc1 .Latt_a_flush
	s_waitcnt vmcnt(0) lgkmcnt(0)
	s_barrier
	s_sub_i32 s73, s73, 64
	s_addk_i32 s9, 0x4000
	s_mov_b32 s14, s13
	s_add_i32 s13, s14, 1
	s_branch .Latt_a_def

.Latt_b_main:
	s_waitcnt lgkmcnt(6)
	v_mfma_f32_32x32x16_bf16 v[132:147], v[180:183], v[184:187], v[148:163]
	ds_read_b128 v[180:183], v249
	ds_read_b128 v[184:187], v219 offset:3072
	s_waitcnt lgkmcnt(6)
	v_mfma_f32_32x32x16_bf16 v[148:163], v[188:191], v[192:195], v[148:163]
	ds_read_b128 v[188:191], v251
	ds_read_b128 v[192:195], v219 offset:5120
	s_waitcnt lgkmcnt(6)
	v_mfma_f32_32x32x16_bf16 v[148:163], v[200:203], v[204:207], v[148:163]
	ds_read_b128 v[200:203], v252
	ds_read_b128 v[204:207], v219 offset:6144
	s_waitcnt lgkmcnt(6)
	v_mfma_f32_32x32x16_bf16 v[148:163], v[208:211], v[212:215], v[148:163]
	ds_read_b128 v[208:211], v253
	ds_read_b128 v[212:215], v219 offset:7168
	s_waitcnt lgkmcnt(6)
	v_mfma_f32_32x32x16_bf16 v[148:163], v[180:183], v[184:187], v[148:163]
	ds_read_b64_tr_b16 v[180:181], v228 offset:32768
	ds_read_b64_tr_b16 v[182:183], v228 offset:33280
	ds_read_b64_tr_b16 v[184:185], v228 offset:33792
	ds_read_b64_tr_b16 v[186:187], v228 offset:34304
	s_waitcnt lgkmcnt(8)
	v_mfma_f32_32x32x16_bf16 v[132:147], v[188:191], v[192:195], v[132:147]
	ds_read_b64_tr_b16 v[188:189], v228 offset:36864
	ds_read_b64_tr_b16 v[190:191], v228 offset:37376
	ds_read_b64_tr_b16 v[192:193], v228 offset:37888
	ds_read_b64_tr_b16 v[194:195], v228 offset:38400
	s_waitcnt lgkmcnt(10)
	v_mfma_f32_32x32x16_bf16 v[132:147], v[200:203], v[204:207], v[132:147]
	ds_read_b64_tr_b16 v[200:201], v228 offset:40960
	ds_read_b64_tr_b16 v[202:203], v228 offset:41472
	ds_read_b64_tr_b16 v[204:205], v228 offset:41984
	ds_read_b64_tr_b16 v[206:207], v228 offset:42496
	s_waitcnt lgkmcnt(12)
	v_mfma_f32_32x32x16_bf16 v[132:147], v[208:211], v[212:215], v[132:147]
	ds_read_b64_tr_b16 v[208:209], v228 offset:45056
	ds_read_b64_tr_b16 v[210:211], v228 offset:45568
	v_exp_f32_e32 v148, v148
	v_exp_f32_e32 v149, v149
	v_exp_f32_e32 v150, v150
	v_exp_f32_e32 v151, v151
	v_exp_f32_e32 v152, v152
	v_exp_f32_e32 v153, v153
	v_exp_f32_e32 v154, v154
	v_exp_f32_e32 v155, v155
	v_exp_f32_e32 v156, v156
	v_exp_f32_e32 v157, v157
	v_exp_f32_e32 v158, v158
	v_exp_f32_e32 v159, v159
	v_exp_f32_e32 v160, v160
	v_exp_f32_e32 v161, v161
	v_exp_f32_e32 v162, v162
	v_exp_f32_e32 v163, v163
	v_add_f32_e32 v170, v170, v148
	v_add_f32_e32 v171, v171, v149
	v_cvt_pk_bf16_f32 v230, v148, v149
	v_add_f32_e32 v170, v170, v150
	v_add_f32_e32 v171, v171, v151
	v_cvt_pk_bf16_f32 v231, v150, v151
	v_add_f32_e32 v170, v170, v152
	v_add_f32_e32 v171, v171, v153
	v_cvt_pk_bf16_f32 v232, v152, v153
	v_add_f32_e32 v170, v170, v154
	v_add_f32_e32 v171, v171, v155
	v_cvt_pk_bf16_f32 v233, v154, v155
	v_add_f32_e32 v170, v170, v156
	v_add_f32_e32 v171, v171, v157
	v_cvt_pk_bf16_f32 v234, v156, v157
	v_add_f32_e32 v170, v170, v158
	v_add_f32_e32 v171, v171, v159
	v_cvt_pk_bf16_f32 v235, v158, v159
	v_add_f32_e32 v170, v170, v160
	v_add_f32_e32 v171, v171, v161
	v_cvt_pk_bf16_f32 v236, v160, v161
	v_add_f32_e32 v170, v170, v162
	v_add_f32_e32 v171, v171, v163
	v_cvt_pk_bf16_f32 v237, v162, v163
	s_waitcnt lgkmcnt(12)
	ds_read_b64_tr_b16 v[212:213], v228 offset:46080
	ds_read_b64_tr_b16 v[214:215], v228 offset:46592
	s_setprio 2
	v_mfma_f32_32x32x16_bf16 v[100:115], v[180:183], v[230:233], v[100:115]
	v_exp_f32_e32 v132, v132
	v_exp_f32_e32 v133, v133
	s_waitcnt lgkmcnt(12)
	v_mfma_f32_32x32x16_bf16 v[100:115], v[184:187], v[234:237], v[100:115]
	v_exp_f32_e32 v134, v134
	v_exp_f32_e32 v135, v135
	v_add_f32_e32 v178, v178, v132
	v_add_f32_e32 v179, v179, v133
	v_cvt_pk_bf16_f32 v238, v132, v133
	s_waitcnt lgkmcnt(10)
	v_mfma_f32_32x32x16_bf16 v[68:83], v[188:191], v[230:233], v[68:83]
	v_exp_f32_e32 v136, v136
	v_exp_f32_e32 v137, v137
	v_add_f32_e32 v178, v178, v134
	v_add_f32_e32 v179, v179, v135
	v_cvt_pk_bf16_f32 v239, v134, v135
	s_waitcnt lgkmcnt(8)
	v_mfma_f32_32x32x16_bf16 v[68:83], v[192:195], v[234:237], v[68:83]
	v_exp_f32_e32 v138, v138
	v_exp_f32_e32 v139, v139
	v_add_f32_e32 v178, v178, v136
	v_add_f32_e32 v179, v179, v137
	v_cvt_pk_bf16_f32 v240, v136, v137
	s_waitcnt lgkmcnt(6)
	v_mfma_f32_32x32x16_bf16 v[34:49], v[200:203], v[230:233], v[34:49]
	v_exp_f32_e32 v140, v140
	v_exp_f32_e32 v141, v141
	v_add_f32_e32 v178, v178, v138
	v_add_f32_e32 v179, v179, v139
	v_cvt_pk_bf16_f32 v241, v138, v139
	s_waitcnt lgkmcnt(4)
	v_mfma_f32_32x32x16_bf16 v[34:49], v[204:207], v[234:237], v[34:49]
	v_exp_f32_e32 v142, v142
	v_exp_f32_e32 v143, v143
	v_add_f32_e32 v178, v178, v140
	v_add_f32_e32 v179, v179, v141
	v_cvt_pk_bf16_f32 v242, v140, v141
	s_waitcnt lgkmcnt(2)
	v_mfma_f32_32x32x16_bf16 v[18:33], v[208:211], v[230:233], v[18:33]
	v_exp_f32_e32 v144, v144
	v_exp_f32_e32 v145, v145
	v_add_f32_e32 v178, v178, v142
	v_add_f32_e32 v179, v179, v143
	v_cvt_pk_bf16_f32 v243, v142, v143
	s_waitcnt lgkmcnt(0)
	v_mfma_f32_32x32x16_bf16 v[18:33], v[212:215], v[234:237], v[18:33]
	v_exp_f32_e32 v146, v146
	v_exp_f32_e32 v147, v147
	v_add_f32_e32 v178, v178, v144
	v_add_f32_e32 v179, v179, v145
	v_cvt_pk_bf16_f32 v244, v144, v145
	s_nop 0
	v_add_f32_e32 v178, v178, v146
	v_add_f32_e32 v179, v179, v147
	v_cvt_pk_bf16_f32 v245, v146, v147
	s_nop 0
	v_mfma_f32_32x32x16_bf16 v[116:131], v[180:183], v[238:241], v[116:131]
	v_add3_u32 v148, s20, v216, 32
	v_sub_u32_e32 v148, v148, v166
	v_mfma_f32_32x32x16_bf16 v[116:131], v[184:187], v[242:245], v[116:131]
	ds_read_b128 v[180:183], v250 offset:8192
	ds_read_b128 v[184:187], v219 offset:4096
	v_cvt_f32_i32_e32 v148, v148
	v_fma_f32 v148, v164, v148, -v221
	v_mfma_f32_32x32x16_bf16 v[84:99], v[188:191], v[238:241], v[84:99]
	v_add_f32_e32 v149, v164, v148
	v_add_f32_e32 v150, v176, v148
	v_add_f32_e32 v151, v177, v149
	v_mfma_f32_32x32x16_bf16 v[84:99], v[192:195], v[242:245], v[84:99]
	ds_read_b128 v[188:191], v246 offset:8192
	ds_read_b128 v[192:195], v219
	v_add_f32_e32 v152, v174, v148
	v_add_f32_e32 v153, v175, v149
	v_add_f32_e32 v154, v174, v150
	v_add_f32_e32 v155, v175, v151
	v_mfma_f32_32x32x16_bf16 v[50:65], v[200:203], v[238:241], v[50:65]
	v_add_f32_e32 v156, v174, v152
	v_add_f32_e32 v157, v175, v153
	v_add_f32_e32 v158, v174, v154
	v_add_f32_e32 v159, v175, v155
	v_mfma_f32_32x32x16_bf16 v[50:65], v[204:207], v[242:245], v[50:65]
	ds_read_b128 v[200:203], v247 offset:8192
	ds_read_b128 v[204:207], v219 offset:1024
	v_add_f32_e32 v160, v174, v156
	v_add_f32_e32 v161, v175, v157
	v_add_f32_e32 v162, v174, v158
	v_add_f32_e32 v163, v175, v159
	v_mfma_f32_32x32x16_bf16 v[2:17], v[208:211], v[238:241], v[2:17]
	v_mfma_f32_32x32x16_bf16 v[2:17], v[212:215], v[242:245], v[2:17]
	ds_read_b128 v[208:211], v248 offset:8192
	ds_read_b128 v[212:215], v219 offset:2048
	s_setprio 0
	s_waitcnt lgkmcnt(6)
	v_mfma_f32_32x32x16_bf16 v[132:147], v[180:183], v[184:187], v[148:163]
	ds_read_b128 v[180:183], v249 offset:8192
	ds_read_b128 v[184:187], v219 offset:3072
	s_waitcnt lgkmcnt(6)
	v_mfma_f32_32x32x16_bf16 v[148:163], v[188:191], v[192:195], v[148:163]
	ds_read_b128 v[188:191], v251 offset:8192
	ds_read_b128 v[192:195], v219 offset:5120
	s_waitcnt lgkmcnt(6)
	v_mfma_f32_32x32x16_bf16 v[148:163], v[200:203], v[204:207], v[148:163]
	ds_read_b128 v[200:203], v252 offset:8192
	ds_read_b128 v[204:207], v219 offset:6144
	s_waitcnt lgkmcnt(6)
	v_mfma_f32_32x32x16_bf16 v[148:163], v[208:211], v[212:215], v[148:163]
	ds_read_b128 v[208:211], v253 offset:8192
	ds_read_b128 v[212:215], v219 offset:7168
	s_waitcnt lgkmcnt(6)
	v_mfma_f32_32x32x16_bf16 v[148:163], v[180:183], v[184:187], v[148:163]
	ds_read_b64_tr_b16 v[180:181], v228 offset:34816
	ds_read_b64_tr_b16 v[182:183], v228 offset:35328
	ds_read_b64_tr_b16 v[184:185], v228 offset:35840
	ds_read_b64_tr_b16 v[186:187], v228 offset:36352
	s_waitcnt lgkmcnt(8)
	v_mfma_f32_32x32x16_bf16 v[132:147], v[188:191], v[192:195], v[132:147]
	ds_read_b64_tr_b16 v[188:189], v228 offset:38912
	ds_read_b64_tr_b16 v[190:191], v228 offset:39424
	ds_read_b64_tr_b16 v[192:193], v228 offset:39936
	ds_read_b64_tr_b16 v[194:195], v228 offset:40448
	s_waitcnt lgkmcnt(10)
	v_mfma_f32_32x32x16_bf16 v[132:147], v[200:203], v[204:207], v[132:147]
	ds_read_b64_tr_b16 v[200:201], v228 offset:43008
	ds_read_b64_tr_b16 v[202:203], v228 offset:43520
	ds_read_b64_tr_b16 v[204:205], v228 offset:44032
	ds_read_b64_tr_b16 v[206:207], v228 offset:44544
	s_waitcnt lgkmcnt(12)
	v_mfma_f32_32x32x16_bf16 v[132:147], v[208:211], v[212:215], v[132:147]
	ds_read_b64_tr_b16 v[208:209], v228 offset:47104
	ds_read_b64_tr_b16 v[210:211], v228 offset:47616
	v_exp_f32_e32 v148, v148
	v_exp_f32_e32 v149, v149
	v_exp_f32_e32 v150, v150
	v_exp_f32_e32 v151, v151
	v_exp_f32_e32 v152, v152
	v_exp_f32_e32 v153, v153
	v_exp_f32_e32 v154, v154
	v_exp_f32_e32 v155, v155
	v_exp_f32_e32 v156, v156
	v_exp_f32_e32 v157, v157
	v_exp_f32_e32 v158, v158
	v_exp_f32_e32 v159, v159
	v_exp_f32_e32 v160, v160
	v_exp_f32_e32 v161, v161
	v_exp_f32_e32 v162, v162
	v_exp_f32_e32 v163, v163
	v_add_f32_e32 v170, v170, v148
	v_add_f32_e32 v171, v171, v149
	v_cvt_pk_bf16_f32 v230, v148, v149
	v_add_f32_e32 v170, v170, v150
	v_add_f32_e32 v171, v171, v151
	v_cvt_pk_bf16_f32 v231, v150, v151
	v_add_f32_e32 v170, v170, v152
	v_add_f32_e32 v171, v171, v153
	v_cvt_pk_bf16_f32 v232, v152, v153
	v_add_f32_e32 v170, v170, v154
	v_add_f32_e32 v171, v171, v155
	v_cvt_pk_bf16_f32 v233, v154, v155
	v_add_f32_e32 v170, v170, v156
	v_add_f32_e32 v171, v171, v157
	v_cvt_pk_bf16_f32 v234, v156, v157
	v_add_f32_e32 v170, v170, v158
	v_add_f32_e32 v171, v171, v159
	v_cvt_pk_bf16_f32 v235, v158, v159
	v_add_f32_e32 v170, v170, v160
	v_add_f32_e32 v171, v171, v161
	v_cvt_pk_bf16_f32 v236, v160, v161
	v_add_f32_e32 v170, v170, v162
	v_add_f32_e32 v171, v171, v163
	v_cvt_pk_bf16_f32 v237, v162, v163
	s_waitcnt lgkmcnt(12)
	ds_read_b64_tr_b16 v[212:213], v228 offset:48128
	ds_read_b64_tr_b16 v[214:215], v228 offset:48640
	s_cmp_ge_i32 s13, s77
	s_cbranch_scc1 .Latt_b_flush
	s_cmp_eq_u32 s13, s78
	s_cbranch_scc1 .Latt_b_flush
	s_waitcnt vmcnt(0) lgkmcnt(0)
	s_barrier
	s_sub_i32 s73, s73, 64
	s_addk_i32 s9, 0x4000
	s_mov_b32 s14, s13
	s_add_i32 s13, s14, 1
	s_branch .Latt_b_def

.Latt_a_def:
	s_and_b32 s15, s9, 0x4000
	s_max_i32 s20, s73, 0
	v_or_b32_e32 v246, s15, v220
	v_xor_b32_e32 v250, 0x80, v246
	v_xor_b32_e32 v247, 32, v246
	v_xor_b32_e32 v248, 64, v246
	s_sub_i32 s38, s73, 64
	s_max_i32 s74, s38, 0
	s_lshl_b64 s[16:17], s[74:75], 12
	s_add_i32 s38, s9, 0x4000
	s_and_b32 s38, s38, 0x4000
	s_add_i32 s39, s38, s10
	s_add_i32 s40, s39, 0x400
	s_add_i32 s41, s38, s11
	s_add_i32 s42, s41, 0x400
	s_mov_b64 s[44:45], 0x10000
	s_mov_b32 s43, m0
	v_xor_b32_e32 v249, 0x60, v246
	v_xor_b32_e32 v251, 0xa0, v246
	v_xor_b32_e32 v252, 0xc0, v246
	v_xor_b32_e32 v253, 0xe0, v246
	v_add_u32_e32 v228, s15, v222
	v_mfma_f32_32x32x16_bf16 v[116:131], v[180:183], v[238:241], v[116:131]
	v_lshl_add_u64 v[132:133], v[172:173], 0, s[16:17]
	s_mov_b32 m0, s39
	s_nop 0
	global_load_lds_dwordx4 v[132:133], off
	v_add_u32_e32 v148, s20, v216
	v_sub_u32_e32 v148, v148, v166
	v_mfma_f32_32x32x16_bf16 v[116:131], v[184:187], v[242:245], v[116:131]
	ds_read_b128 v[180:183], v250
	ds_read_b128 v[184:187], v219 offset:4096
	v_cvt_f32_i32_e32 v148, v148
	v_fma_f32 v148, v164, v148, -v221
	v_mfma_f32_32x32x16_bf16 v[84:99], v[188:191], v[238:241], v[84:99]
	v_lshl_add_u64 v[132:133], v[132:133], 0, v[66:67]
	s_mov_b32 m0, s40
	s_nop 0
	global_load_lds_dwordx4 v[132:133], off
	v_add_f32_e32 v149, v164, v148
	v_add_f32_e32 v150, v176, v148
	v_add_f32_e32 v151, v177, v149
	v_mfma_f32_32x32x16_bf16 v[84:99], v[192:195], v[242:245], v[84:99]
	ds_read_b128 v[188:191], v246
	ds_read_b128 v[192:195], v219
	v_add_f32_e32 v152, v174, v148
	v_add_f32_e32 v153, v175, v149
	v_add_f32_e32 v154, v174, v150
	v_add_f32_e32 v155, v175, v151
	v_mfma_f32_32x32x16_bf16 v[50:65], v[200:203], v[238:241], v[50:65]
	v_lshl_add_u64 v[134:135], v[168:169], 0, s[16:17]
	s_mov_b32 m0, s41
	s_nop 0
	global_load_lds_dwordx4 v[134:135], off
	v_add_f32_e32 v156, v174, v152
	v_add_f32_e32 v157, v175, v153
	v_add_f32_e32 v158, v174, v154
	v_add_f32_e32 v159, v175, v155
	v_mfma_f32_32x32x16_bf16 v[50:65], v[204:207], v[242:245], v[50:65]
	ds_read_b128 v[200:203], v247
	ds_read_b128 v[204:207], v219 offset:1024
	v_add_f32_e32 v160, v174, v156
	v_add_f32_e32 v161, v175, v157
	v_add_f32_e32 v162, v174, v158
	v_add_f32_e32 v163, v175, v159
	v_mfma_f32_32x32x16_bf16 v[2:17], v[208:211], v[238:241], v[2:17]
	v_lshl_add_u64 v[134:135], v[134:135], 0, s[44:45]
	s_mov_b32 m0, s42
	s_nop 0
	global_load_lds_dwordx4 v[134:135], off
	s_mov_b32 m0, s43
	v_mfma_f32_32x32x16_bf16 v[2:17], v[212:215], v[242:245], v[2:17]
	ds_read_b128 v[208:211], v248
	ds_read_b128 v[212:215], v219 offset:2048
	s_setprio 0
	s_branch .Latt_a_main
.Latt_b_def:
	s_and_b32 s15, s9, 0x4000
	s_max_i32 s20, s73, 0
	v_or_b32_e32 v246, s15, v220
	v_xor_b32_e32 v250, 0x80, v246
	v_xor_b32_e32 v247, 32, v246
	v_xor_b32_e32 v248, 64, v246
	s_sub_i32 s38, s73, 64
	s_max_i32 s74, s38, 0
	s_lshl_b64 s[16:17], s[74:75], 12
	s_add_i32 s38, s9, 0x4000
	s_and_b32 s38, s38, 0x4000
	s_add_i32 s39, s38, s10
	s_add_i32 s40, s39, 0x400
	s_add_i32 s41, s38, s11
	s_add_i32 s42, s41, 0x400
	s_mov_b64 s[44:45], 0x10000
	s_mov_b32 s43, m0
	v_xor_b32_e32 v249, 0x60, v246
	v_xor_b32_e32 v251, 0xa0, v246
	v_xor_b32_e32 v252, 0xc0, v246
	v_xor_b32_e32 v253, 0xe0, v246
	v_add_u32_e32 v228, s15, v222
	s_setprio 2
	v_mfma_f32_32x32x16_bf16 v[100:115], v[180:183], v[230:233], v[100:115]
	v_exp_f32_e32 v132, v132
	v_exp_f32_e32 v133, v133
	s_waitcnt lgkmcnt(12)
	v_mfma_f32_32x32x16_bf16 v[100:115], v[184:187], v[234:237], v[100:115]
	v_exp_f32_e32 v134, v134
	v_exp_f32_e32 v135, v135
	v_add_f32_e32 v178, v178, v132
	v_add_f32_e32 v179, v179, v133
	v_cvt_pk_bf16_f32 v238, v132, v133
	s_waitcnt lgkmcnt(10)
	v_mfma_f32_32x32x16_bf16 v[68:83], v[188:191], v[230:233], v[68:83]
	v_exp_f32_e32 v136, v136
	v_exp_f32_e32 v137, v137
	v_add_f32_e32 v178, v178, v134
	v_add_f32_e32 v179, v179, v135
	v_cvt_pk_bf16_f32 v239, v134, v135
	s_waitcnt lgkmcnt(8)
	v_mfma_f32_32x32x16_bf16 v[68:83], v[192:195], v[234:237], v[68:83]
	v_exp_f32_e32 v138, v138
	v_exp_f32_e32 v139, v139
	v_add_f32_e32 v178, v178, v136
	v_add_f32_e32 v179, v179, v137
	v_cvt_pk_bf16_f32 v240, v136, v137
	s_waitcnt lgkmcnt(6)
	v_mfma_f32_32x32x16_bf16 v[34:49], v[200:203], v[230:233], v[34:49]
	v_exp_f32_e32 v140, v140
	v_exp_f32_e32 v141, v141
	v_add_f32_e32 v178, v178, v138
	v_add_f32_e32 v179, v179, v139
	v_cvt_pk_bf16_f32 v241, v138, v139
	s_waitcnt lgkmcnt(4)
	v_mfma_f32_32x32x16_bf16 v[34:49], v[204:207], v[234:237], v[34:49]
	v_exp_f32_e32 v142, v142
	v_exp_f32_e32 v143, v143
	v_add_f32_e32 v178, v178, v140
	v_add_f32_e32 v179, v179, v141
	v_cvt_pk_bf16_f32 v242, v140, v141
	s_waitcnt lgkmcnt(2)
	v_mfma_f32_32x32x16_bf16 v[18:33], v[208:211], v[230:233], v[18:33]
	v_exp_f32_e32 v144, v144
	v_exp_f32_e32 v145, v145
	v_add_f32_e32 v178, v178, v142
	v_add_f32_e32 v179, v179, v143
	v_cvt_pk_bf16_f32 v243, v142, v143
	s_waitcnt lgkmcnt(0)
	v_mfma_f32_32x32x16_bf16 v[18:33], v[212:215], v[234:237], v[18:33]
	v_exp_f32_e32 v146, v146
	v_exp_f32_e32 v147, v147
	v_add_f32_e32 v178, v178, v144
	v_add_f32_e32 v179, v179, v145
	v_cvt_pk_bf16_f32 v244, v144, v145
	s_nop 0
	v_add_f32_e32 v178, v178, v146
	v_add_f32_e32 v179, v179, v147
	v_cvt_pk_bf16_f32 v245, v146, v147
	s_nop 0
	v_mfma_f32_32x32x16_bf16 v[116:131], v[180:183], v[238:241], v[116:131]
	v_lshl_add_u64 v[132:133], v[172:173], 0, s[16:17]
	s_mov_b32 m0, s39
	s_nop 0
	global_load_lds_dwordx4 v[132:133], off
	v_add_u32_e32 v148, s20, v216
	v_sub_u32_e32 v148, v148, v166
	v_mfma_f32_32x32x16_bf16 v[116:131], v[184:187], v[242:245], v[116:131]
	ds_read_b128 v[180:183], v250
	ds_read_b128 v[184:187], v219 offset:4096
	v_cvt_f32_i32_e32 v148, v148
	v_fma_f32 v148, v164, v148, -v221
	v_mfma_f32_32x32x16_bf16 v[84:99], v[188:191], v[238:241], v[84:99]
	v_lshl_add_u64 v[132:133], v[132:133], 0, v[66:67]
	s_mov_b32 m0, s40
	s_nop 0
	global_load_lds_dwordx4 v[132:133], off
	v_add_f32_e32 v149, v164, v148
	v_add_f32_e32 v150, v176, v148
	v_add_f32_e32 v151, v177, v149
	v_mfma_f32_32x32x16_bf16 v[84:99], v[192:195], v[242:245], v[84:99]
	ds_read_b128 v[188:191], v246
	ds_read_b128 v[192:195], v219
	v_add_f32_e32 v152, v174, v148
	v_add_f32_e32 v153, v175, v149
	v_add_f32_e32 v154, v174, v150
	v_add_f32_e32 v155, v175, v151
	v_mfma_f32_32x32x16_bf16 v[50:65], v[200:203], v[238:241], v[50:65]
	v_lshl_add_u64 v[134:135], v[168:169], 0, s[16:17]
	s_mov_b32 m0, s41
	s_nop 0
	global_load_lds_dwordx4 v[134:135], off
	v_add_f32_e32 v156, v174, v152
	v_add_f32_e32 v157, v175, v153
	v_add_f32_e32 v158, v174, v154
	v_add_f32_e32 v159, v175, v155
	v_mfma_f32_32x32x16_bf16 v[50:65], v[204:207], v[242:245], v[50:65]
	ds_read_b128 v[200:203], v247
	ds_read_b128 v[204:207], v219 offset:1024
	v_add_f32_e32 v160, v174, v156
	v_add_f32_e32 v161, v175, v157
	v_add_f32_e32 v162, v174, v158
	v_add_f32_e32 v163, v175, v159
	v_mfma_f32_32x32x16_bf16 v[2:17], v[208:211], v[238:241], v[2:17]
	v_lshl_add_u64 v[134:135], v[134:135], 0, s[44:45]
	s_mov_b32 m0, s42
	s_nop 0
	global_load_lds_dwordx4 v[134:135], off
	s_mov_b32 m0, s43
	v_mfma_f32_32x32x16_bf16 v[2:17], v[212:215], v[242:245], v[2:17]
	ds_read_b128 v[208:211], v248
	ds_read_b128 v[212:215], v219 offset:2048
	s_setprio 0
	s_branch .Latt_b_main
.Latt_first:
	s_and_b32 s15, s9, 0x4000
	s_max_i32 s20, s73, 0
	v_or_b32_e32 v246, s15, v220
	v_xor_b32_e32 v250, 0x80, v246
	v_xor_b32_e32 v247, 32, v246
	v_xor_b32_e32 v248, 64, v246
	s_sub_i32 s38, s73, 64
	s_max_i32 s74, s38, 0
	s_lshl_b64 s[16:17], s[74:75], 12
	s_add_i32 s38, s9, 0x4000
	s_and_b32 s38, s38, 0x4000
	s_add_i32 s39, s38, s10
	s_add_i32 s40, s39, 0x400
	s_add_i32 s41, s38, s11
	s_add_i32 s42, s41, 0x400
	s_mov_b64 s[44:45], 0x10000
	s_mov_b32 s43, m0
	ds_read_b128 v[180:183], v250
	ds_read_b128 v[184:187], v219 offset:4096
	ds_read_b128 v[188:191], v246
	ds_read_b128 v[192:195], v219
	ds_read_b128 v[200:203], v247
	ds_read_b128 v[204:207], v219 offset:1024
	ds_read_b128 v[208:211], v248
	ds_read_b128 v[212:215], v219 offset:2048
	v_lshl_add_u64 v[132:133], v[172:173], 0, s[16:17]
	s_mov_b32 m0, s39
	s_nop 0
	global_load_lds_dwordx4 v[132:133], off
	v_lshl_add_u64 v[132:133], v[132:133], 0, v[66:67]
	s_mov_b32 m0, s40
	s_nop 0
	global_load_lds_dwordx4 v[132:133], off
	v_lshl_add_u64 v[134:135], v[168:169], 0, s[16:17]
	s_mov_b32 m0, s41
	s_nop 0
	global_load_lds_dwordx4 v[134:135], off
	v_lshl_add_u64 v[134:135], v[134:135], 0, s[44:45]
	s_mov_b32 m0, s42
	s_nop 0
	global_load_lds_dwordx4 v[134:135], off
	s_mov_b32 m0, s43
	v_add_u32_e32 v148, s20, v216
	v_sub_u32_e32 v148, v148, v166
	v_cvt_f32_i32_e32 v148, v148
	v_mul_f32_e32 v148, v164, v148
	v_add_f32_e32 v149, v164, v148
	v_add_f32_e32 v150, v164, v149
	v_add_f32_e32 v151, v164, v150
	v_add_f32_e32 v152, v223, v151
	v_add_f32_e32 v153, v164, v152
	v_add_f32_e32 v154, v164, v153
	v_add_f32_e32 v155, v164, v154
	v_add_f32_e32 v156, v223, v155
	v_add_f32_e32 v157, v164, v156
	v_add_f32_e32 v158, v164, v157
	v_add_f32_e32 v159, v164, v158
	v_add_f32_e32 v160, v223, v159
	v_add_f32_e32 v161, v164, v160
	v_add_f32_e32 v162, v164, v161
	v_add_f32_e32 v163, v164, v162
	v_sub_f32_e64 v148, -|v148|, v221
	v_sub_f32_e64 v149, -|v149|, v221
	v_sub_f32_e64 v150, -|v150|, v221
	v_sub_f32_e64 v151, -|v151|, v221
	v_sub_f32_e64 v152, -|v152|, v221
	v_sub_f32_e64 v153, -|v153|, v221
	v_sub_f32_e64 v154, -|v154|, v221
	v_sub_f32_e64 v155, -|v155|, v221
	v_sub_f32_e64 v156, -|v156|, v221
	v_sub_f32_e64 v157, -|v157|, v221
	v_sub_f32_e64 v158, -|v158|, v221
	v_sub_f32_e64 v159, -|v159|, v221
	v_sub_f32_e64 v160, -|v160|, v221
	v_sub_f32_e64 v161, -|v161|, v221
	v_sub_f32_e64 v162, -|v162|, v221
	v_sub_f32_e64 v163, -|v163|, v221
	v_xor_b32_e32 v249, 0x60, v246
	v_xor_b32_e32 v251, 0xa0, v246
	v_xor_b32_e32 v252, 0xc0, v246
	v_xor_b32_e32 v253, 0xe0, v246
	v_add_u32_e32 v228, s15, v222
	s_waitcnt lgkmcnt(6)
	v_mfma_f32_32x32x16_bf16 v[132:147], v[180:183], v[184:187], v[148:163]
	ds_read_b128 v[180:183], v249
	ds_read_b128 v[184:187], v219 offset:3072
	s_waitcnt lgkmcnt(6)
	v_mfma_f32_32x32x16_bf16 v[148:163], v[188:191], v[192:195], v[148:163]
	ds_read_b128 v[188:191], v251
	ds_read_b128 v[192:195], v219 offset:5120
	s_waitcnt lgkmcnt(6)
	v_mfma_f32_32x32x16_bf16 v[148:163], v[200:203], v[204:207], v[148:163]
	ds_read_b128 v[200:203], v252
	ds_read_b128 v[204:207], v219 offset:6144
	s_waitcnt lgkmcnt(6)
	v_mfma_f32_32x32x16_bf16 v[148:163], v[208:211], v[212:215], v[148:163]
	ds_read_b128 v[208:211], v253
	ds_read_b128 v[212:215], v219 offset:7168
	s_waitcnt lgkmcnt(6)
	v_mfma_f32_32x32x16_bf16 v[148:163], v[180:183], v[184:187], v[148:163]
	ds_read_b64_tr_b16 v[180:181], v228 offset:32768
	ds_read_b64_tr_b16 v[182:183], v228 offset:33280
	ds_read_b64_tr_b16 v[184:185], v228 offset:33792
	ds_read_b64_tr_b16 v[186:187], v228 offset:34304
	s_waitcnt lgkmcnt(8)
	v_mfma_f32_32x32x16_bf16 v[132:147], v[188:191], v[192:195], v[132:147]
	ds_read_b64_tr_b16 v[188:189], v228 offset:36864
	ds_read_b64_tr_b16 v[190:191], v228 offset:37376
	ds_read_b64_tr_b16 v[192:193], v228 offset:37888
	ds_read_b64_tr_b16 v[194:195], v228 offset:38400
	s_waitcnt lgkmcnt(10)
	v_mfma_f32_32x32x16_bf16 v[132:147], v[200:203], v[204:207], v[132:147]
	ds_read_b64_tr_b16 v[200:201], v228 offset:40960
	ds_read_b64_tr_b16 v[202:203], v228 offset:41472
	ds_read_b64_tr_b16 v[204:205], v228 offset:41984
	ds_read_b64_tr_b16 v[206:207], v228 offset:42496
	s_waitcnt lgkmcnt(12)
	v_mfma_f32_32x32x16_bf16 v[132:147], v[208:211], v[212:215], v[132:147]
	ds_read_b64_tr_b16 v[208:209], v228 offset:45056
	ds_read_b64_tr_b16 v[210:211], v228 offset:45568
	v_exp_f32_e32 v148, v148
	v_exp_f32_e32 v149, v149
	v_exp_f32_e32 v150, v150
	v_exp_f32_e32 v151, v151
	v_exp_f32_e32 v152, v152
	v_exp_f32_e32 v153, v153
	v_exp_f32_e32 v154, v154
	v_exp_f32_e32 v155, v155
	v_exp_f32_e32 v156, v156
	v_exp_f32_e32 v157, v157
	v_exp_f32_e32 v158, v158
	v_exp_f32_e32 v159, v159
	v_exp_f32_e32 v160, v160
	v_exp_f32_e32 v161, v161
	v_exp_f32_e32 v162, v162
	v_exp_f32_e32 v163, v163
	v_add_f32_e32 v170, v170, v148
	v_add_f32_e32 v171, v171, v149
	v_cvt_pk_bf16_f32 v230, v148, v149
	v_add_f32_e32 v170, v170, v150
	v_add_f32_e32 v171, v171, v151
	v_cvt_pk_bf16_f32 v231, v150, v151
	v_add_f32_e32 v170, v170, v152
	v_add_f32_e32 v171, v171, v153
	v_cvt_pk_bf16_f32 v232, v152, v153
	v_add_f32_e32 v170, v170, v154
	v_add_f32_e32 v171, v171, v155
	v_cvt_pk_bf16_f32 v233, v154, v155
	v_add_f32_e32 v170, v170, v156
	v_add_f32_e32 v171, v171, v157
	v_cvt_pk_bf16_f32 v234, v156, v157
	v_add_f32_e32 v170, v170, v158
	v_add_f32_e32 v171, v171, v159
	v_cvt_pk_bf16_f32 v235, v158, v159
	v_add_f32_e32 v170, v170, v160
	v_add_f32_e32 v171, v171, v161
	v_cvt_pk_bf16_f32 v236, v160, v161
	v_add_f32_e32 v170, v170, v162
	v_add_f32_e32 v171, v171, v163
	v_cvt_pk_bf16_f32 v237, v162, v163
	s_waitcnt lgkmcnt(12)
	ds_read_b64_tr_b16 v[212:213], v228 offset:46080
	ds_read_b64_tr_b16 v[214:215], v228 offset:46592
	s_setprio 2
	v_mfma_f32_32x32x16_bf16 v[100:115], v[180:183], v[230:233], v[100:115]
	v_exp_f32_e32 v132, v132
	v_exp_f32_e32 v133, v133
	s_waitcnt lgkmcnt(12)
	v_mfma_f32_32x32x16_bf16 v[100:115], v[184:187], v[234:237], v[100:115]
	v_exp_f32_e32 v134, v134
	v_exp_f32_e32 v135, v135
	v_add_f32_e32 v178, v178, v132
	v_add_f32_e32 v179, v179, v133
	v_cvt_pk_bf16_f32 v238, v132, v133
	s_waitcnt lgkmcnt(10)
	v_mfma_f32_32x32x16_bf16 v[68:83], v[188:191], v[230:233], v[68:83]
	v_exp_f32_e32 v136, v136
	v_exp_f32_e32 v137, v137
	v_add_f32_e32 v178, v178, v134
	v_add_f32_e32 v179, v179, v135
	v_cvt_pk_bf16_f32 v239, v134, v135
	s_waitcnt lgkmcnt(8)
	v_mfma_f32_32x32x16_bf16 v[68:83], v[192:195], v[234:237], v[68:83]
	v_exp_f32_e32 v138, v138
	v_exp_f32_e32 v139, v139
	v_add_f32_e32 v178, v178, v136
	v_add_f32_e32 v179, v179, v137
	v_cvt_pk_bf16_f32 v240, v136, v137
	s_waitcnt lgkmcnt(6)
	v_mfma_f32_32x32x16_bf16 v[34:49], v[200:203], v[230:233], v[34:49]
	v_exp_f32_e32 v140, v140
	v_exp_f32_e32 v141, v141
	v_add_f32_e32 v178, v178, v138
	v_add_f32_e32 v179, v179, v139
	v_cvt_pk_bf16_f32 v241, v138, v139
	s_waitcnt lgkmcnt(4)
	v_mfma_f32_32x32x16_bf16 v[34:49], v[204:207], v[234:237], v[34:49]
	v_exp_f32_e32 v142, v142
	v_exp_f32_e32 v143, v143
	v_add_f32_e32 v178, v178, v140
	v_add_f32_e32 v179, v179, v141
	v_cvt_pk_bf16_f32 v242, v140, v141
	s_waitcnt lgkmcnt(2)
	v_mfma_f32_32x32x16_bf16 v[18:33], v[208:211], v[230:233], v[18:33]
	v_exp_f32_e32 v144, v144
	v_exp_f32_e32 v145, v145
	v_add_f32_e32 v178, v178, v142
	v_add_f32_e32 v179, v179, v143
	v_cvt_pk_bf16_f32 v243, v142, v143
	s_waitcnt lgkmcnt(0)
	v_mfma_f32_32x32x16_bf16 v[18:33], v[212:215], v[234:237], v[18:33]
	v_exp_f32_e32 v146, v146
	v_exp_f32_e32 v147, v147
	v_add_f32_e32 v178, v178, v144
	v_add_f32_e32 v179, v179, v145
	v_cvt_pk_bf16_f32 v244, v144, v145
	s_nop 0
	v_add_f32_e32 v178, v178, v146
	v_add_f32_e32 v179, v179, v147
	v_cvt_pk_bf16_f32 v245, v146, v147
	s_nop 0
	v_mfma_f32_32x32x16_bf16 v[116:131], v[180:183], v[238:241], v[116:131]
	v_mfma_f32_32x32x16_bf16 v[116:131], v[184:187], v[242:245], v[116:131]
	ds_read_b128 v[180:183], v250 offset:8192
	ds_read_b128 v[184:187], v219 offset:4096
	v_mfma_f32_32x32x16_bf16 v[84:99], v[188:191], v[238:241], v[84:99]
	v_mfma_f32_32x32x16_bf16 v[84:99], v[192:195], v[242:245], v[84:99]
	ds_read_b128 v[188:191], v246 offset:8192
	ds_read_b128 v[192:195], v219
	v_mfma_f32_32x32x16_bf16 v[50:65], v[200:203], v[238:241], v[50:65]
	v_mfma_f32_32x32x16_bf16 v[50:65], v[204:207], v[242:245], v[50:65]
	ds_read_b128 v[200:203], v247 offset:8192
	ds_read_b128 v[204:207], v219 offset:1024
	v_mfma_f32_32x32x16_bf16 v[2:17], v[208:211], v[238:241], v[2:17]
	v_mfma_f32_32x32x16_bf16 v[2:17], v[212:215], v[242:245], v[2:17]
	ds_read_b128 v[208:211], v248 offset:8192
	ds_read_b128 v[212:215], v219 offset:2048
	s_setprio 0
	v_add3_u32 v148, s20, v216, 32
	v_sub_u32_e32 v148, v148, v166
	v_cvt_f32_i32_e32 v148, v148
	v_mul_f32_e32 v148, v164, v148
	v_add_f32_e32 v149, v164, v148
	v_add_f32_e32 v150, v164, v149
	v_add_f32_e32 v151, v164, v150
	v_add_f32_e32 v152, v223, v151
	v_add_f32_e32 v153, v164, v152
	v_add_f32_e32 v154, v164, v153
	v_add_f32_e32 v155, v164, v154
	v_add_f32_e32 v156, v223, v155
	v_add_f32_e32 v157, v164, v156
	v_add_f32_e32 v158, v164, v157
	v_add_f32_e32 v159, v164, v158
	v_add_f32_e32 v160, v223, v159
	v_add_f32_e32 v161, v164, v160
	v_add_f32_e32 v162, v164, v161
	v_add_f32_e32 v163, v164, v162
	v_sub_f32_e64 v148, -|v148|, v221
	v_sub_f32_e64 v149, -|v149|, v221
	v_sub_f32_e64 v150, -|v150|, v221
	v_sub_f32_e64 v151, -|v151|, v221
	v_sub_f32_e64 v152, -|v152|, v221
	v_sub_f32_e64 v153, -|v153|, v221
	v_sub_f32_e64 v154, -|v154|, v221
	v_sub_f32_e64 v155, -|v155|, v221
	v_sub_f32_e64 v156, -|v156|, v221
	v_sub_f32_e64 v157, -|v157|, v221
	v_sub_f32_e64 v158, -|v158|, v221
	v_sub_f32_e64 v159, -|v159|, v221
	v_sub_f32_e64 v160, -|v160|, v221
	v_sub_f32_e64 v161, -|v161|, v221
	v_sub_f32_e64 v162, -|v162|, v221
	v_sub_f32_e64 v163, -|v163|, v221
	s_nop 1
	s_waitcnt lgkmcnt(6)
	v_mfma_f32_32x32x16_bf16 v[132:147], v[180:183], v[184:187], v[148:163]
	ds_read_b128 v[180:183], v249 offset:8192
	ds_read_b128 v[184:187], v219 offset:3072
	s_waitcnt lgkmcnt(6)
	v_mfma_f32_32x32x16_bf16 v[148:163], v[188:191], v[192:195], v[148:163]
	ds_read_b128 v[188:191], v251 offset:8192
	ds_read_b128 v[192:195], v219 offset:5120
	s_waitcnt lgkmcnt(6)
	v_mfma_f32_32x32x16_bf16 v[148:163], v[200:203], v[204:207], v[148:163]
	ds_read_b128 v[200:203], v252 offset:8192
	ds_read_b128 v[204:207], v219 offset:6144
	s_waitcnt lgkmcnt(6)
	v_mfma_f32_32x32x16_bf16 v[148:163], v[208:211], v[212:215], v[148:163]
	ds_read_b128 v[208:211], v253 offset:8192
	ds_read_b128 v[212:215], v219 offset:7168
	s_waitcnt lgkmcnt(6)
	v_mfma_f32_32x32x16_bf16 v[148:163], v[180:183], v[184:187], v[148:163]
	ds_read_b64_tr_b16 v[180:181], v228 offset:34816
	ds_read_b64_tr_b16 v[182:183], v228 offset:35328
	ds_read_b64_tr_b16 v[184:185], v228 offset:35840
	ds_read_b64_tr_b16 v[186:187], v228 offset:36352
	s_waitcnt lgkmcnt(8)
	v_mfma_f32_32x32x16_bf16 v[132:147], v[188:191], v[192:195], v[132:147]
	ds_read_b64_tr_b16 v[188:189], v228 offset:38912
	ds_read_b64_tr_b16 v[190:191], v228 offset:39424
	ds_read_b64_tr_b16 v[192:193], v228 offset:39936
	ds_read_b64_tr_b16 v[194:195], v228 offset:40448
	s_waitcnt lgkmcnt(10)
	v_mfma_f32_32x32x16_bf16 v[132:147], v[200:203], v[204:207], v[132:147]
	ds_read_b64_tr_b16 v[200:201], v228 offset:43008
	ds_read_b64_tr_b16 v[202:203], v228 offset:43520
	ds_read_b64_tr_b16 v[204:205], v228 offset:44032
	ds_read_b64_tr_b16 v[206:207], v228 offset:44544
	s_waitcnt lgkmcnt(12)
	v_mfma_f32_32x32x16_bf16 v[132:147], v[208:211], v[212:215], v[132:147]
	ds_read_b64_tr_b16 v[208:209], v228 offset:47104
	ds_read_b64_tr_b16 v[210:211], v228 offset:47616
	v_exp_f32_e32 v148, v148
	v_exp_f32_e32 v149, v149
	v_exp_f32_e32 v150, v150
	v_exp_f32_e32 v151, v151
	v_exp_f32_e32 v152, v152
	v_exp_f32_e32 v153, v153
	v_exp_f32_e32 v154, v154
	v_exp_f32_e32 v155, v155
	v_exp_f32_e32 v156, v156
	v_exp_f32_e32 v157, v157
	v_exp_f32_e32 v158, v158
	v_exp_f32_e32 v159, v159
	v_exp_f32_e32 v160, v160
	v_exp_f32_e32 v161, v161
	v_exp_f32_e32 v162, v162
	v_exp_f32_e32 v163, v163
	v_add_f32_e32 v170, v170, v148
	v_add_f32_e32 v171, v171, v149
	v_cvt_pk_bf16_f32 v230, v148, v149
	v_add_f32_e32 v170, v170, v150
	v_add_f32_e32 v171, v171, v151
	v_cvt_pk_bf16_f32 v231, v150, v151
	v_add_f32_e32 v170, v170, v152
	v_add_f32_e32 v171, v171, v153
	v_cvt_pk_bf16_f32 v232, v152, v153
	v_add_f32_e32 v170, v170, v154
	v_add_f32_e32 v171, v171, v155
	v_cvt_pk_bf16_f32 v233, v154, v155
	v_add_f32_e32 v170, v170, v156
	v_add_f32_e32 v171, v171, v157
	v_cvt_pk_bf16_f32 v234, v156, v157
	v_add_f32_e32 v170, v170, v158
	v_add_f32_e32 v171, v171, v159
	v_cvt_pk_bf16_f32 v235, v158, v159
	v_add_f32_e32 v170, v170, v160
	v_add_f32_e32 v171, v171, v161
	v_cvt_pk_bf16_f32 v236, v160, v161
	v_add_f32_e32 v170, v170, v162
	v_add_f32_e32 v171, v171, v163
	v_cvt_pk_bf16_f32 v237, v162, v163
	s_waitcnt lgkmcnt(12)
	ds_read_b64_tr_b16 v[212:213], v228 offset:48128
	ds_read_b64_tr_b16 v[214:215], v228 offset:48640
	s_cmp_le_i32 s12, 1
	s_cbranch_scc1 .Latt_first_b
	s_setprio 2
	v_mfma_f32_32x32x16_bf16 v[100:115], v[180:183], v[230:233], v[100:115]
	v_exp_f32_e32 v132, v132
	v_exp_f32_e32 v133, v133
	s_waitcnt lgkmcnt(12)
	v_mfma_f32_32x32x16_bf16 v[100:115], v[184:187], v[234:237], v[100:115]
	v_exp_f32_e32 v134, v134
	v_exp_f32_e32 v135, v135
	v_add_f32_e32 v178, v178, v132
	v_add_f32_e32 v179, v179, v133
	v_cvt_pk_bf16_f32 v238, v132, v133
	s_waitcnt lgkmcnt(10)
	v_mfma_f32_32x32x16_bf16 v[68:83], v[188:191], v[230:233], v[68:83]
	v_exp_f32_e32 v136, v136
	v_exp_f32_e32 v137, v137
	v_add_f32_e32 v178, v178, v134
	v_add_f32_e32 v179, v179, v135
	v_cvt_pk_bf16_f32 v239, v134, v135
	s_waitcnt lgkmcnt(8)
	v_mfma_f32_32x32x16_bf16 v[68:83], v[192:195], v[234:237], v[68:83]
	v_exp_f32_e32 v138, v138
	v_exp_f32_e32 v139, v139
	v_add_f32_e32 v178, v178, v136
	v_add_f32_e32 v179, v179, v137
	v_cvt_pk_bf16_f32 v240, v136, v137
	s_waitcnt lgkmcnt(6)
	v_mfma_f32_32x32x16_bf16 v[34:49], v[200:203], v[230:233], v[34:49]
	v_exp_f32_e32 v140, v140
	v_exp_f32_e32 v141, v141
	v_add_f32_e32 v178, v178, v138
	v_add_f32_e32 v179, v179, v139
	v_cvt_pk_bf16_f32 v241, v138, v139
	s_waitcnt lgkmcnt(4)
	v_mfma_f32_32x32x16_bf16 v[34:49], v[204:207], v[234:237], v[34:49]
	v_exp_f32_e32 v142, v142
	v_exp_f32_e32 v143, v143
	v_add_f32_e32 v178, v178, v140
	v_add_f32_e32 v179, v179, v141
	v_cvt_pk_bf16_f32 v242, v140, v141
	s_waitcnt lgkmcnt(2)
	v_mfma_f32_32x32x16_bf16 v[18:33], v[208:211], v[230:233], v[18:33]
	v_exp_f32_e32 v144, v144
	v_exp_f32_e32 v145, v145
	v_add_f32_e32 v178, v178, v142
	v_add_f32_e32 v179, v179, v143
	v_cvt_pk_bf16_f32 v243, v142, v143
	s_waitcnt lgkmcnt(0)
	v_mfma_f32_32x32x16_bf16 v[18:33], v[212:215], v[234:237], v[18:33]
	v_exp_f32_e32 v146, v146
	v_exp_f32_e32 v147, v147
	v_add_f32_e32 v178, v178, v144
	v_add_f32_e32 v179, v179, v145
	v_cvt_pk_bf16_f32 v244, v144, v145
	s_nop 0
	v_add_f32_e32 v178, v178, v146
	v_add_f32_e32 v179, v179, v147
	v_cvt_pk_bf16_f32 v245, v146, v147
	s_nop 0
	s_cmp_ge_i32 s13, s77
	s_cbranch_scc1 .Latt_fa_flush
	s_cmp_eq_u32 s13, s78
	s_cbranch_scc1 .Latt_fa_flush
	s_waitcnt vmcnt(0) lgkmcnt(0)
	s_barrier
	s_sub_i32 s73, s73, 64
	s_addk_i32 s9, 0x4000
	s_mov_b32 s14, s13
	s_add_i32 s13, s14, 1
	s_branch .Latt_a_def

.Latt_first_b:
	s_cmp_ge_i32 s13, s77
	s_cbranch_scc1 .Latt_fb_flush
	s_cmp_eq_u32 s13, s78
	s_cbranch_scc1 .Latt_fb_flush
	s_waitcnt vmcnt(0) lgkmcnt(0)
	s_barrier
	s_sub_i32 s73, s73, 64
	s_addk_i32 s9, 0x4000
	s_mov_b32 s14, s13
	s_add_i32 s13, s14, 1
	s_branch .Latt_b_def
